# hand-written P3 scan loop (saddr addressing, double-buffered loads); GEMM2 gate loads issued before first wait
# speedup vs baseline: 1.0079x; 1.0079x over previous
; __device__ __forceinline__ unsigned f2bf(float f) { unsigned u = __builtin_bit_cast(unsigned, f); return (u + 0x7fffu + ((u >> 16) & 1u)) >> 16; }
; __device__ __forceinline__ void h2_phase(const Ptrs& P, int G, int tid) {
;     ...
;     for (int idx = blockIdx.x * 512 + tid; idx < NH * HD * (HD / 2); idx += G * 512) {
;         const int d2 = idx & 63, e = (idx >> 6) & 127, h = idx >> 13;
;         const size_t off = ((size_t)h * HD + e) * HD + 2 * d2;
;         float s0 = 0.f, s1 = 0.f;
;         for (int nb = 0; nb < NCH; nb += UB) {
;             h16x2 l[UB]; f32x2 dd[UB];
; #pragma unroll
;             for (int q = 0; q < UB; ++q) { l[q] = *(const h16x2*)(P.L + (size_t)(nb + q) * SLAB + off); dd[q] = *(const f32x2*)(P.Dn + (size_t)((nb + q) * NH + h) * HD + 2 * d2); }
; #pragma unroll
;             for (int q = 0; q < UB; ++q) {
;                 *(unsigned*)(P.S + (size_t)(nb + q) * SLAB + off) = f2bf(s0) | (f2bf(s1) << 16);
;                 s0 = dd[q][0] * s0 + (float)l[q][0]; s1 = dd[q][1] * s1 + (float)l[q][1]; }
;         }
.LBB0_294:
	v_ashrrev_i32_e32 v2, 13, v28
	v_lshlrev_b32_e32 v0, 1, v29
	v_ashrrev_i32_e32 v3, 31, v2
	v_lshlrev_b32_e32 v4, 2, v29
	v_and_b32_e32 v6, 0x7f00, v0
	v_and_b32_e32 v7, 0xfc, v0
	v_lshlrev_b64 v[0:1], 9, v[2:3]
	v_and_or_b32 v0, v4, s22, v0
	v_lshlrev_b64 v[4:5], 15, v[2:3]
	v_or3_b32 v4, v4, v6, v7
	v_mov_b32_e32 v6, 0
	v_mov_b32_e32 v7, 0
	s_mov_b64 s[18:19], s[12:13]
	s_mov_b64 s[20:21], s[14:15]
	s_mov_b64 s[22:23], s[10:11]
	s_mov_b32 s26, 7
	s_add_u32 s24, s18, 0x0
	s_addc_u32 s25, s19, 0
	global_load_dword v32, v4, s[24:25]
	s_add_u32 s24, s22, 0x0
	s_addc_u32 s25, s23, 0
	global_load_dwordx2 v[48:49], v0, s[24:25]
	s_add_u32 s24, s18, 0x80000
	s_addc_u32 s25, s19, 0
	global_load_dword v33, v4, s[24:25]
	s_add_u32 s24, s22, 0x2000
	s_addc_u32 s25, s23, 0
	global_load_dwordx2 v[50:51], v0, s[24:25]
	s_add_u32 s24, s18, 0x100000
	s_addc_u32 s25, s19, 0
	global_load_dword v34, v4, s[24:25]
	s_add_u32 s24, s22, 0x4000
	s_addc_u32 s25, s23, 0
	global_load_dwordx2 v[52:53], v0, s[24:25]
	s_add_u32 s24, s18, 0x180000
	s_addc_u32 s25, s19, 0
	global_load_dword v35, v4, s[24:25]
	s_add_u32 s24, s22, 0x6000
	s_addc_u32 s25, s23, 0
	global_load_dwordx2 v[54:55], v0, s[24:25]
	s_add_u32 s24, s18, 0x200000
	s_addc_u32 s25, s19, 0
	global_load_dword v36, v4, s[24:25]
	s_add_u32 s24, s22, 0x8000
	s_addc_u32 s25, s23, 0
	global_load_dwordx2 v[56:57], v0, s[24:25]
	s_add_u32 s24, s18, 0x280000
	s_addc_u32 s25, s19, 0
	global_load_dword v37, v4, s[24:25]
	s_add_u32 s24, s22, 0xa000
	s_addc_u32 s25, s23, 0
	global_load_dwordx2 v[58:59], v0, s[24:25]
	s_add_u32 s24, s18, 0x300000
	s_addc_u32 s25, s19, 0
	global_load_dword v38, v4, s[24:25]
	s_add_u32 s24, s22, 0xc000
	s_addc_u32 s25, s23, 0
	global_load_dwordx2 v[60:61], v0, s[24:25]
	s_add_u32 s24, s18, 0x380000
	s_addc_u32 s25, s19, 0
	global_load_dword v39, v4, s[24:25]
	s_add_u32 s24, s22, 0xe000
	s_addc_u32 s25, s23, 0
	global_load_dwordx2 v[62:63], v0, s[24:25]
	s_add_u32 s18, s18, 0x400000
	s_addc_u32 s19, s19, 0
	s_add_u32 s22, s22, 0x10000
	s_addc_u32 s23, s23, 0
	s_add_u32 s24, s18, 0x0
	s_addc_u32 s25, s19, 0
	global_load_dword v40, v4, s[24:25]
	s_add_u32 s24, s22, 0x0
	s_addc_u32 s25, s23, 0
	global_load_dwordx2 v[64:65], v0, s[24:25]
	s_add_u32 s24, s18, 0x80000
	s_addc_u32 s25, s19, 0
	global_load_dword v41, v4, s[24:25]
	s_add_u32 s24, s22, 0x2000
	s_addc_u32 s25, s23, 0
	global_load_dwordx2 v[66:67], v0, s[24:25]
	s_add_u32 s24, s18, 0x100000
	s_addc_u32 s25, s19, 0
	global_load_dword v42, v4, s[24:25]
	s_add_u32 s24, s22, 0x4000
	s_addc_u32 s25, s23, 0
	global_load_dwordx2 v[68:69], v0, s[24:25]
	s_add_u32 s24, s18, 0x180000
	s_addc_u32 s25, s19, 0
	global_load_dword v43, v4, s[24:25]
	s_add_u32 s24, s22, 0x6000
	s_addc_u32 s25, s23, 0
	global_load_dwordx2 v[70:71], v0, s[24:25]
	s_add_u32 s24, s18, 0x200000
	s_addc_u32 s25, s19, 0
	global_load_dword v44, v4, s[24:25]
	s_add_u32 s24, s22, 0x8000
	s_addc_u32 s25, s23, 0
	global_load_dwordx2 v[72:73], v0, s[24:25]
	s_add_u32 s24, s18, 0x280000
	s_addc_u32 s25, s19, 0
	global_load_dword v45, v4, s[24:25]
	s_add_u32 s24, s22, 0xa000
	s_addc_u32 s25, s23, 0
	global_load_dwordx2 v[74:75], v0, s[24:25]
	s_add_u32 s24, s18, 0x300000
	s_addc_u32 s25, s19, 0
	global_load_dword v46, v4, s[24:25]
	s_add_u32 s24, s22, 0xc000
	s_addc_u32 s25, s23, 0
	global_load_dwordx2 v[76:77], v0, s[24:25]
	s_add_u32 s24, s18, 0x380000
	s_addc_u32 s25, s19, 0
	global_load_dword v47, v4, s[24:25]
	s_add_u32 s24, s22, 0xe000
	s_addc_u32 s25, s23, 0
	global_load_dwordx2 v[78:79], v0, s[24:25]
	s_add_u32 s18, s18, 0x400000
	s_addc_u32 s19, s19, 0
	s_add_u32 s22, s22, 0x10000
	s_addc_u32 s23, s23, 0
	s_waitcnt vmcnt(16)
.Lp3_loop:
	s_waitcnt vmcnt(38)
	v_cvt_pk_bf16_f32 v8, v6, v7
	s_add_u32 s24, s20, 0x0
	s_addc_u32 s25, s21, 0
	global_store_dword v4, v8, s[24:25]
	v_cvt_f32_f16_e32 v9, v32
	v_cvt_f32_f16_sdwa v10, v32 dst_sel:DWORD dst_unused:UNUSED_PAD src0_sel:WORD_1
	v_fma_f32 v6, v48, v6, v9
	v_fma_f32 v7, v49, v7, v10
	s_waitcnt vmcnt(37)
	v_cvt_pk_bf16_f32 v11, v6, v7
	s_add_u32 s24, s20, 0x80000
	s_addc_u32 s25, s21, 0
	global_store_dword v4, v11, s[24:25]
	v_cvt_f32_f16_e32 v9, v33
	v_cvt_f32_f16_sdwa v10, v33 dst_sel:DWORD dst_unused:UNUSED_PAD src0_sel:WORD_1
	v_fma_f32 v6, v50, v6, v9
	v_fma_f32 v7, v51, v7, v10
	s_waitcnt vmcnt(36)
	v_cvt_pk_bf16_f32 v8, v6, v7
	s_add_u32 s24, s20, 0x100000
	s_addc_u32 s25, s21, 0
	global_store_dword v4, v8, s[24:25]
	v_cvt_f32_f16_e32 v9, v34
	v_cvt_f32_f16_sdwa v10, v34 dst_sel:DWORD dst_unused:UNUSED_PAD src0_sel:WORD_1
	v_fma_f32 v6, v52, v6, v9
	v_fma_f32 v7, v53, v7, v10
	s_waitcnt vmcnt(35)
	v_cvt_pk_bf16_f32 v11, v6, v7
	s_add_u32 s24, s20, 0x180000
	s_addc_u32 s25, s21, 0
	global_store_dword v4, v11, s[24:25]
	v_cvt_f32_f16_e32 v9, v35
	v_cvt_f32_f16_sdwa v10, v35 dst_sel:DWORD dst_unused:UNUSED_PAD src0_sel:WORD_1
	v_fma_f32 v6, v54, v6, v9
	v_fma_f32 v7, v55, v7, v10
	s_waitcnt vmcnt(34)
	v_cvt_pk_bf16_f32 v8, v6, v7
	s_add_u32 s24, s20, 0x200000
	s_addc_u32 s25, s21, 0
	global_store_dword v4, v8, s[24:25]
	v_cvt_f32_f16_e32 v9, v36
	v_cvt_f32_f16_sdwa v10, v36 dst_sel:DWORD dst_unused:UNUSED_PAD src0_sel:WORD_1
	v_fma_f32 v6, v56, v6, v9
	v_fma_f32 v7, v57, v7, v10
	s_waitcnt vmcnt(33)
	v_cvt_pk_bf16_f32 v11, v6, v7
	s_add_u32 s24, s20, 0x280000
	s_addc_u32 s25, s21, 0
	global_store_dword v4, v11, s[24:25]
	v_cvt_f32_f16_e32 v9, v37
	v_cvt_f32_f16_sdwa v10, v37 dst_sel:DWORD dst_unused:UNUSED_PAD src0_sel:WORD_1
	v_fma_f32 v6, v58, v6, v9
	v_fma_f32 v7, v59, v7, v10
	s_waitcnt vmcnt(32)
; __device__ __forceinline__ unsigned f2bf(float f) { unsigned u = __builtin_bit_cast(unsigned, f); return (u + 0x7fffu + ((u >> 16) & 1u)) >> 16; }
; __device__ __forceinline__ void h2_phase(const Ptrs& P, int G, int tid) {
;     ...
;         for (int nb = 0; nb < NCH; nb += UB) {
;             h16x2 l[UB]; f32x2 dd[UB];
; #pragma unroll
;             for (int q = 0; q < UB; ++q) { l[q] = *(const h16x2*)(P.L + (size_t)(nb + q) * SLAB + off); dd[q] = *(const f32x2*)(P.Dn + (size_t)((nb + q) * NH + h) * HD + 2 * d2); }
; #pragma unroll
;             for (int q = 0; q < UB; ++q) {
;                 *(unsigned*)(P.S + (size_t)(nb + q) * SLAB + off) = f2bf(s0) | (f2bf(s1) << 16);
;                 s0 = dd[q][0] * s0 + (float)l[q][0]; s1 = dd[q][1] * s1 + (float)l[q][1]; }
;         }
	v_cvt_pk_bf16_f32 v8, v6, v7
	s_add_u32 s24, s20, 0x300000
	s_addc_u32 s25, s21, 0
	global_store_dword v4, v8, s[24:25]
	v_cvt_f32_f16_e32 v9, v38
	v_cvt_f32_f16_sdwa v10, v38 dst_sel:DWORD dst_unused:UNUSED_PAD src0_sel:WORD_1
	v_fma_f32 v6, v60, v6, v9
	v_fma_f32 v7, v61, v7, v10
	s_waitcnt vmcnt(31)
	v_cvt_pk_bf16_f32 v11, v6, v7
	s_add_u32 s24, s20, 0x380000
	s_addc_u32 s25, s21, 0
	global_store_dword v4, v11, s[24:25]
	v_cvt_f32_f16_e32 v9, v39
	v_cvt_f32_f16_sdwa v10, v39 dst_sel:DWORD dst_unused:UNUSED_PAD src0_sel:WORD_1
	v_fma_f32 v6, v62, v6, v9
	v_fma_f32 v7, v63, v7, v10
	s_add_u32 s20, s20, 0x400000
	s_addc_u32 s21, s21, 0
	s_add_u32 s24, s18, 0x0
	s_addc_u32 s25, s19, 0
	global_load_dword v32, v4, s[24:25]
	s_add_u32 s24, s22, 0x0
	s_addc_u32 s25, s23, 0
	global_load_dwordx2 v[48:49], v0, s[24:25]
	s_add_u32 s24, s18, 0x80000
	s_addc_u32 s25, s19, 0
	global_load_dword v33, v4, s[24:25]
	s_add_u32 s24, s22, 0x2000
	s_addc_u32 s25, s23, 0
	global_load_dwordx2 v[50:51], v0, s[24:25]
	s_add_u32 s24, s18, 0x100000
	s_addc_u32 s25, s19, 0
	global_load_dword v34, v4, s[24:25]
	s_add_u32 s24, s22, 0x4000
	s_addc_u32 s25, s23, 0
	global_load_dwordx2 v[52:53], v0, s[24:25]
	s_add_u32 s24, s18, 0x180000
	s_addc_u32 s25, s19, 0
	global_load_dword v35, v4, s[24:25]
	s_add_u32 s24, s22, 0x6000
	s_addc_u32 s25, s23, 0
	global_load_dwordx2 v[54:55], v0, s[24:25]
	s_add_u32 s24, s18, 0x200000
	s_addc_u32 s25, s19, 0
	global_load_dword v36, v4, s[24:25]
	s_add_u32 s24, s22, 0x8000
	s_addc_u32 s25, s23, 0
	global_load_dwordx2 v[56:57], v0, s[24:25]
	s_add_u32 s24, s18, 0x280000
	s_addc_u32 s25, s19, 0
	global_load_dword v37, v4, s[24:25]
	s_add_u32 s24, s22, 0xa000
	s_addc_u32 s25, s23, 0
	global_load_dwordx2 v[58:59], v0, s[24:25]
	s_add_u32 s24, s18, 0x300000
	s_addc_u32 s25, s19, 0
	global_load_dword v38, v4, s[24:25]
	s_add_u32 s24, s22, 0xc000
	s_addc_u32 s25, s23, 0
	global_load_dwordx2 v[60:61], v0, s[24:25]
	s_add_u32 s24, s18, 0x380000
	s_addc_u32 s25, s19, 0
	global_load_dword v39, v4, s[24:25]
	s_add_u32 s24, s22, 0xe000
	s_addc_u32 s25, s23, 0
	global_load_dwordx2 v[62:63], v0, s[24:25]
	s_add_u32 s18, s18, 0x400000
	s_addc_u32 s19, s19, 0
	s_add_u32 s22, s22, 0x10000
	s_addc_u32 s23, s23, 0
	s_waitcnt vmcnt(38)
	v_cvt_pk_bf16_f32 v8, v6, v7
	s_add_u32 s24, s20, 0x0
	s_addc_u32 s25, s21, 0
	global_store_dword v4, v8, s[24:25]
	v_cvt_f32_f16_e32 v9, v40
	v_cvt_f32_f16_sdwa v10, v40 dst_sel:DWORD dst_unused:UNUSED_PAD src0_sel:WORD_1
	v_fma_f32 v6, v64, v6, v9
	v_fma_f32 v7, v65, v7, v10
	s_waitcnt vmcnt(37)
	v_cvt_pk_bf16_f32 v11, v6, v7
	s_add_u32 s24, s20, 0x80000
	s_addc_u32 s25, s21, 0
	global_store_dword v4, v11, s[24:25]
	v_cvt_f32_f16_e32 v9, v41
	v_cvt_f32_f16_sdwa v10, v41 dst_sel:DWORD dst_unused:UNUSED_PAD src0_sel:WORD_1
	v_fma_f32 v6, v66, v6, v9
	v_fma_f32 v7, v67, v7, v10
	s_waitcnt vmcnt(36)
	v_cvt_pk_bf16_f32 v8, v6, v7
	s_add_u32 s24, s20, 0x100000
	s_addc_u32 s25, s21, 0
	global_store_dword v4, v8, s[24:25]
	v_cvt_f32_f16_e32 v9, v42
	v_cvt_f32_f16_sdwa v10, v42 dst_sel:DWORD dst_unused:UNUSED_PAD src0_sel:WORD_1
	v_fma_f32 v6, v68, v6, v9
	v_fma_f32 v7, v69, v7, v10
	s_waitcnt vmcnt(35)
	v_cvt_pk_bf16_f32 v11, v6, v7
	s_add_u32 s24, s20, 0x180000
	s_addc_u32 s25, s21, 0
	global_store_dword v4, v11, s[24:25]
	v_cvt_f32_f16_e32 v9, v43
	v_cvt_f32_f16_sdwa v10, v43 dst_sel:DWORD dst_unused:UNUSED_PAD src0_sel:WORD_1
	v_fma_f32 v6, v70, v6, v9
	v_fma_f32 v7, v71, v7, v10
	s_waitcnt vmcnt(34)
	v_cvt_pk_bf16_f32 v8, v6, v7
	s_add_u32 s24, s20, 0x200000
	s_addc_u32 s25, s21, 0
	global_store_dword v4, v8, s[24:25]
	v_cvt_f32_f16_e32 v9, v44
	v_cvt_f32_f16_sdwa v10, v44 dst_sel:DWORD dst_unused:UNUSED_PAD src0_sel:WORD_1
	v_fma_f32 v6, v72, v6, v9
	v_fma_f32 v7, v73, v7, v10
	s_waitcnt vmcnt(33)
	v_cvt_pk_bf16_f32 v11, v6, v7
	s_add_u32 s24, s20, 0x280000
	s_addc_u32 s25, s21, 0
	global_store_dword v4, v11, s[24:25]
	v_cvt_f32_f16_e32 v9, v45
	v_cvt_f32_f16_sdwa v10, v45 dst_sel:DWORD dst_unused:UNUSED_PAD src0_sel:WORD_1
	v_fma_f32 v6, v74, v6, v9
	v_fma_f32 v7, v75, v7, v10
	s_waitcnt vmcnt(32)
	v_cvt_pk_bf16_f32 v8, v6, v7
	s_add_u32 s24, s20, 0x300000
	s_addc_u32 s25, s21, 0
	global_store_dword v4, v8, s[24:25]
	v_cvt_f32_f16_e32 v9, v46
	v_cvt_f32_f16_sdwa v10, v46 dst_sel:DWORD dst_unused:UNUSED_PAD src0_sel:WORD_1
	v_fma_f32 v6, v76, v6, v9
	v_fma_f32 v7, v77, v7, v10
	s_waitcnt vmcnt(31)
	v_cvt_pk_bf16_f32 v11, v6, v7
	s_add_u32 s24, s20, 0x380000
	s_addc_u32 s25, s21, 0
	global_store_dword v4, v11, s[24:25]
	v_cvt_f32_f16_e32 v9, v47
	v_cvt_f32_f16_sdwa v10, v47 dst_sel:DWORD dst_unused:UNUSED_PAD src0_sel:WORD_1
	v_fma_f32 v6, v78, v6, v9
	v_fma_f32 v7, v79, v7, v10
	s_add_u32 s20, s20, 0x400000
	s_addc_u32 s21, s21, 0
	s_add_u32 s24, s18, 0x0
	s_addc_u32 s25, s19, 0
	global_load_dword v40, v4, s[24:25]
	s_add_u32 s24, s22, 0x0
	s_addc_u32 s25, s23, 0
	global_load_dwordx2 v[64:65], v0, s[24:25]
	s_add_u32 s24, s18, 0x80000
	s_addc_u32 s25, s19, 0
	global_load_dword v41, v4, s[24:25]
	s_add_u32 s24, s22, 0x2000
	s_addc_u32 s25, s23, 0
	global_load_dwordx2 v[66:67], v0, s[24:25]
	s_add_u32 s24, s18, 0x100000
	s_addc_u32 s25, s19, 0
	global_load_dword v42, v4, s[24:25]
	s_add_u32 s24, s22, 0x4000
	s_addc_u32 s25, s23, 0
	global_load_dwordx2 v[68:69], v0, s[24:25]
	s_add_u32 s24, s18, 0x180000
	s_addc_u32 s25, s19, 0
	global_load_dword v43, v4, s[24:25]
	s_add_u32 s24, s22, 0x6000
	s_addc_u32 s25, s23, 0
	global_load_dwordx2 v[70:71], v0, s[24:25]
	s_add_u32 s24, s18, 0x200000
	s_addc_u32 s25, s19, 0
	global_load_dword v44, v4, s[24:25]
	s_add_u32 s24, s22, 0x8000
	s_addc_u32 s25, s23, 0
	global_load_dwordx2 v[72:73], v0, s[24:25]
	s_add_u32 s24, s18, 0x280000
	s_addc_u32 s25, s19, 0
	global_load_dword v45, v4, s[24:25]
	s_add_u32 s24, s22, 0xa000
	s_addc_u32 s25, s23, 0
	global_load_dwordx2 v[74:75], v0, s[24:25]
	s_add_u32 s24, s18, 0x300000
	s_addc_u32 s25, s19, 0
	global_load_dword v46, v4, s[24:25]
	s_add_u32 s24, s22, 0xc000
	s_addc_u32 s25, s23, 0
	global_load_dwordx2 v[76:77], v0, s[24:25]
	s_add_u32 s24, s18, 0x380000
	s_addc_u32 s25, s19, 0
	global_load_dword v47, v4, s[24:25]
	s_add_u32 s24, s22, 0xe000
	s_addc_u32 s25, s23, 0
	global_load_dwordx2 v[78:79], v0, s[24:25]
	s_add_u32 s18, s18, 0x400000
	s_addc_u32 s19, s19, 0
	s_add_u32 s22, s22, 0x10000
	s_addc_u32 s23, s23, 0
	s_sub_u32 s26, s26, 1
	s_cmp_lg_u32 s26, 0
	s_cbranch_scc1 .Lp3_loop
; __device__ __forceinline__ unsigned f2bf(float f) { unsigned u = __builtin_bit_cast(unsigned, f); return (u + 0x7fffu + ((u >> 16) & 1u)) >> 16; }
; __device__ __forceinline__ void h2_phase(const Ptrs& P, int G, int tid) {
;     ...
;     for (int idx = blockIdx.x * 512 + tid; idx < NH * HD * (HD / 2); idx += G * 512) {
;         const int d2 = idx & 63, e = (idx >> 6) & 127, h = idx >> 13;
;         const size_t off = ((size_t)h * HD + e) * HD + 2 * d2;
;         float s0 = 0.f, s1 = 0.f;
;         for (int nb = 0; nb < NCH; nb += UB) {
;             h16x2 l[UB]; f32x2 dd[UB];
; #pragma unroll
;             for (int q = 0; q < UB; ++q) { l[q] = *(const h16x2*)(P.L + (size_t)(nb + q) * SLAB + off); dd[q] = *(const f32x2*)(P.Dn + (size_t)((nb + q) * NH + h) * HD + 2 * d2); }
; #pragma unroll
;             for (int q = 0; q < UB; ++q) {
;                 *(unsigned*)(P.S + (size_t)(nb + q) * SLAB + off) = f2bf(s0) | (f2bf(s1) << 16);
;                 s0 = dd[q][0] * s0 + (float)l[q][0]; s1 = dd[q][1] * s1 + (float)l[q][1]; }
;         }
;     }
	s_waitcnt vmcnt(38)
	v_cvt_pk_bf16_f32 v8, v6, v7
	s_add_u32 s24, s20, 0x0
	s_addc_u32 s25, s21, 0
	global_store_dword v4, v8, s[24:25]
	v_cvt_f32_f16_e32 v9, v32
	v_cvt_f32_f16_sdwa v10, v32 dst_sel:DWORD dst_unused:UNUSED_PAD src0_sel:WORD_1
	v_fma_f32 v6, v48, v6, v9
	v_fma_f32 v7, v49, v7, v10
	s_waitcnt vmcnt(37)
	v_cvt_pk_bf16_f32 v11, v6, v7
	s_add_u32 s24, s20, 0x80000
	s_addc_u32 s25, s21, 0
	global_store_dword v4, v11, s[24:25]
	v_cvt_f32_f16_e32 v9, v33
	v_cvt_f32_f16_sdwa v10, v33 dst_sel:DWORD dst_unused:UNUSED_PAD src0_sel:WORD_1
	v_fma_f32 v6, v50, v6, v9
	v_fma_f32 v7, v51, v7, v10
	s_waitcnt vmcnt(36)
	v_cvt_pk_bf16_f32 v8, v6, v7
	s_add_u32 s24, s20, 0x100000
	s_addc_u32 s25, s21, 0
	global_store_dword v4, v8, s[24:25]
	v_cvt_f32_f16_e32 v9, v34
	v_cvt_f32_f16_sdwa v10, v34 dst_sel:DWORD dst_unused:UNUSED_PAD src0_sel:WORD_1
	v_fma_f32 v6, v52, v6, v9
	v_fma_f32 v7, v53, v7, v10
	s_waitcnt vmcnt(35)
	v_cvt_pk_bf16_f32 v11, v6, v7
	s_add_u32 s24, s20, 0x180000
	s_addc_u32 s25, s21, 0
	global_store_dword v4, v11, s[24:25]
	v_cvt_f32_f16_e32 v9, v35
	v_cvt_f32_f16_sdwa v10, v35 dst_sel:DWORD dst_unused:UNUSED_PAD src0_sel:WORD_1
	v_fma_f32 v6, v54, v6, v9
	v_fma_f32 v7, v55, v7, v10
	s_waitcnt vmcnt(34)
	v_cvt_pk_bf16_f32 v8, v6, v7
	s_add_u32 s24, s20, 0x200000
	s_addc_u32 s25, s21, 0
	global_store_dword v4, v8, s[24:25]
	v_cvt_f32_f16_e32 v9, v36
	v_cvt_f32_f16_sdwa v10, v36 dst_sel:DWORD dst_unused:UNUSED_PAD src0_sel:WORD_1
	v_fma_f32 v6, v56, v6, v9
	v_fma_f32 v7, v57, v7, v10
	s_waitcnt vmcnt(33)
	v_cvt_pk_bf16_f32 v11, v6, v7
	s_add_u32 s24, s20, 0x280000
	s_addc_u32 s25, s21, 0
	global_store_dword v4, v11, s[24:25]
	v_cvt_f32_f16_e32 v9, v37
	v_cvt_f32_f16_sdwa v10, v37 dst_sel:DWORD dst_unused:UNUSED_PAD src0_sel:WORD_1
	v_fma_f32 v6, v58, v6, v9
	v_fma_f32 v7, v59, v7, v10
	s_waitcnt vmcnt(32)
	v_cvt_pk_bf16_f32 v8, v6, v7
	s_add_u32 s24, s20, 0x300000
	s_addc_u32 s25, s21, 0
	global_store_dword v4, v8, s[24:25]
	v_cvt_f32_f16_e32 v9, v38
	v_cvt_f32_f16_sdwa v10, v38 dst_sel:DWORD dst_unused:UNUSED_PAD src0_sel:WORD_1
	v_fma_f32 v6, v60, v6, v9
	v_fma_f32 v7, v61, v7, v10
	s_waitcnt vmcnt(31)
	v_cvt_pk_bf16_f32 v11, v6, v7
	s_add_u32 s24, s20, 0x380000
	s_addc_u32 s25, s21, 0
	global_store_dword v4, v11, s[24:25]
	v_cvt_f32_f16_e32 v9, v39
	v_cvt_f32_f16_sdwa v10, v39 dst_sel:DWORD dst_unused:UNUSED_PAD src0_sel:WORD_1
	v_fma_f32 v6, v62, v6, v9
	v_fma_f32 v7, v63, v7, v10
	s_add_u32 s20, s20, 0x400000
	s_addc_u32 s21, s21, 0
	s_waitcnt vmcnt(8)
	v_cvt_pk_bf16_f32 v8, v6, v7
	s_add_u32 s24, s20, 0x0
	s_addc_u32 s25, s21, 0
	global_store_dword v4, v8, s[24:25]
	v_cvt_f32_f16_e32 v9, v40
	v_cvt_f32_f16_sdwa v10, v40 dst_sel:DWORD dst_unused:UNUSED_PAD src0_sel:WORD_1
	v_fma_f32 v6, v64, v6, v9
	v_fma_f32 v7, v65, v7, v10
	v_cvt_pk_bf16_f32 v11, v6, v7
	s_add_u32 s24, s20, 0x80000
	s_addc_u32 s25, s21, 0
	global_store_dword v4, v11, s[24:25]
	v_cvt_f32_f16_e32 v9, v41
	v_cvt_f32_f16_sdwa v10, v41 dst_sel:DWORD dst_unused:UNUSED_PAD src0_sel:WORD_1
	v_fma_f32 v6, v66, v6, v9
	v_fma_f32 v7, v67, v7, v10
	v_cvt_pk_bf16_f32 v8, v6, v7
	s_add_u32 s24, s20, 0x100000
	s_addc_u32 s25, s21, 0
	global_store_dword v4, v8, s[24:25]
	v_cvt_f32_f16_e32 v9, v42
	v_cvt_f32_f16_sdwa v10, v42 dst_sel:DWORD dst_unused:UNUSED_PAD src0_sel:WORD_1
	v_fma_f32 v6, v68, v6, v9
	v_fma_f32 v7, v69, v7, v10
	v_cvt_pk_bf16_f32 v11, v6, v7
	s_add_u32 s24, s20, 0x180000
	s_addc_u32 s25, s21, 0
	global_store_dword v4, v11, s[24:25]
	v_cvt_f32_f16_e32 v9, v43
	v_cvt_f32_f16_sdwa v10, v43 dst_sel:DWORD dst_unused:UNUSED_PAD src0_sel:WORD_1
	v_fma_f32 v6, v70, v6, v9
	v_fma_f32 v7, v71, v7, v10
	v_cvt_pk_bf16_f32 v8, v6, v7
	s_add_u32 s24, s20, 0x200000
	s_addc_u32 s25, s21, 0
	global_store_dword v4, v8, s[24:25]
	v_cvt_f32_f16_e32 v9, v44
	v_cvt_f32_f16_sdwa v10, v44 dst_sel:DWORD dst_unused:UNUSED_PAD src0_sel:WORD_1
	v_fma_f32 v6, v72, v6, v9
	v_fma_f32 v7, v73, v7, v10
	v_cvt_pk_bf16_f32 v11, v6, v7
	s_add_u32 s24, s20, 0x280000
	s_addc_u32 s25, s21, 0
	global_store_dword v4, v11, s[24:25]
	v_cvt_f32_f16_e32 v9, v45
	v_cvt_f32_f16_sdwa v10, v45 dst_sel:DWORD dst_unused:UNUSED_PAD src0_sel:WORD_1
	v_fma_f32 v6, v74, v6, v9
	v_fma_f32 v7, v75, v7, v10
	v_cvt_pk_bf16_f32 v8, v6, v7
	s_add_u32 s24, s20, 0x300000
	s_addc_u32 s25, s21, 0
	global_store_dword v4, v8, s[24:25]
	v_cvt_f32_f16_e32 v9, v46
	v_cvt_f32_f16_sdwa v10, v46 dst_sel:DWORD dst_unused:UNUSED_PAD src0_sel:WORD_1
	v_fma_f32 v6, v76, v6, v9
	v_fma_f32 v7, v77, v7, v10
	v_cvt_pk_bf16_f32 v11, v6, v7
	s_add_u32 s24, s20, 0x380000
	s_addc_u32 s25, s21, 0
	global_store_dword v4, v11, s[24:25]
	v_cvt_f32_f16_e32 v9, v47
	v_cvt_f32_f16_sdwa v10, v47 dst_sel:DWORD dst_unused:UNUSED_PAD src0_sel:WORD_1
	v_fma_f32 v6, v78, v6, v9
	v_fma_f32 v7, v79, v7, v10
	s_add_u32 s20, s20, 0x400000
	s_addc_u32 s21, s21, 0
	v_add_u32_e32 v28, s6, v28
	v_cmp_lt_i32_e32 vcc, s54, v28
	s_or_b64 s[16:17], vcc, s[16:17]
	v_add_u32_e32 v29, s7, v29
	s_andn2_b64 exec, exec, s[16:17]
	s_cbranch_execnz .LBB0_294

;     __device__ __forceinline__ void operator()(f32x4 (&acc)[2][2][4][2], const Unit& u, int wr, int wc, int fr, int fq) const {
;     ...
;         const h16* gbase = PG + (size_t)(u.pm * 32 + 2 * u.pn) * 65536 + (u.half == 0 ? 0 : 32768) + (wr * 4 + wc) * 512 + (fq * 16 + fr) * 8;
; #pragma unroll
;         for (int ai = 0; ai < 2; ++ai) {
;             h16x8 gt[4][2];
; #pragma unroll
;             for (int m = 0; m < 4; ++m)
; #pragma unroll
;                 for (int bj = 0; bj < 2; ++bj) gt[m][bj] = *(const h16x8*)(gbase + (size_t)bj * 65536 + (ai * 4 + m) * 4096);
;             if (u.half == 0) {
; #pragma unroll
;                 for (int m = 0; m < 4; ++m)
; #pragma unroll
;                     for (int bj = 0; bj < 2; ++bj)
; #pragma unroll
;                         for (int j = 0; j < 4; ++j) { acc[ai][bj][m][0][j] *= (float)gt[m][bj][j]; acc[ai][bj][m][1][j] *= (float)gt[m][bj][4 + j]; }
.LBB0_474:
	s_lshl_b32 s4, s44, 5
	s_lshl_b32 s5, s45, 1
	s_add_i32 s4, s4, s5
	s_ashr_i32 s5, s4, 31
	s_lshl_b64 s[4:5], s[4:5], 17
	s_add_u32 s27, s61, s4
	s_addc_u32 s29, s62, s5
	s_cmp_lg_u32 s80, 0
	s_cselect_b64 s[46:47], -1, 0
	s_cmp_eq_u32 s80, 0
	s_cselect_b64 s[4:5], -1, 0
	s_and_b64 s[4:5], s[4:5], exec
	s_cselect_b32 s48, 0, 0x10000
	s_add_u32 s27, s27, s48
	s_addc_u32 s29, s29, 0
	s_add_u32 s48, s27, s18
	s_addc_u32 s49, s29, s19
	v_lshl_add_u64 v[146:147], s[48:49], 0, v[132:133]
	v_add_co_u32_e32 v142, vcc, s72, v146
	global_load_dwordx4 v[148:151], v132, s[48:49] nt
	s_nop 0
	v_addc_co_u32_e32 v143, vcc, 0, v147, vcc
	global_load_dwordx4 v[152:155], v[142:143], off nt
	v_add_co_u32_e32 v142, vcc, s59, v146
	v_lshl_add_u32 v144, s44, 8, v213
	s_nop 0
	v_addc_co_u32_e32 v143, vcc, 0, v147, vcc
	global_load_dwordx4 v[156:159], v[142:143], off nt
	v_add_co_u32_e32 v142, vcc, 0x22000, v146
	v_ashrrev_i32_e32 v145, 31, v144
	s_nop 0
	v_addc_co_u32_e32 v143, vcc, 0, v147, vcc
	global_load_dwordx4 v[160:163], v[142:143], off nt
	v_add_co_u32_e32 v142, vcc, s60, v146
	s_nop 1
	v_addc_co_u32_e32 v143, vcc, 0, v147, vcc
	global_load_dwordx4 v[164:167], v[142:143], off nt
	v_add_co_u32_e32 v142, vcc, 0x24000, v146
	s_nop 1
	v_addc_co_u32_e32 v143, vcc, 0, v147, vcc
	global_load_dwordx4 v[218:221], v[142:143], off nt
	v_add_co_u32_e32 v142, vcc, 0x6000, v146
	s_nop 1
	v_addc_co_u32_e32 v143, vcc, 0, v147, vcc
	global_load_dwordx4 v[222:225], v[142:143], off nt
	v_add_co_u32_e32 v142, vcc, 0x26000, v146
	s_nop 1
	v_addc_co_u32_e32 v143, vcc, 0, v147, vcc
	global_load_dwordx4 v[226:229], v[142:143], off nt
	s_waitcnt vmcnt(4)
	v_cvt_f32_f16_sdwa v205, v150 dst_sel:DWORD dst_unused:UNUSED_PAD src0_sel:WORD_1
	v_cvt_f32_f16_e32 v208, v148
	v_cvt_f32_f16_e32 v204, v150
	v_cvt_f32_f16_sdwa v209, v148 dst_sel:DWORD dst_unused:UNUSED_PAD src0_sel:WORD_1
	v_cvt_f32_f16_e32 v210, v149
	v_cvt_f32_f16_e32 v206, v151
	v_cvt_f32_f16_sdwa v211, v149 dst_sel:DWORD dst_unused:UNUSED_PAD src0_sel:WORD_1
	v_cvt_f32_f16_sdwa v207, v151 dst_sel:DWORD dst_unused:UNUSED_PAD src0_sel:WORD_1
	v_cvt_f32_f16_e32 v200, v152
	v_cvt_f32_f16_e32 v196, v154
	v_cvt_f32_f16_sdwa v201, v152 dst_sel:DWORD dst_unused:UNUSED_PAD src0_sel:WORD_1
	v_cvt_f32_f16_sdwa v197, v154 dst_sel:DWORD dst_unused:UNUSED_PAD src0_sel:WORD_1
	v_cvt_f32_f16_e32 v202, v153
	v_cvt_f32_f16_e32 v198, v155
	v_cvt_f32_f16_sdwa v203, v153 dst_sel:DWORD dst_unused:UNUSED_PAD src0_sel:WORD_1
	v_cvt_f32_f16_sdwa v199, v155 dst_sel:DWORD dst_unused:UNUSED_PAD src0_sel:WORD_1
	v_cvt_f32_f16_e32 v192, v156
	v_cvt_f32_f16_e32 v188, v158
	v_cvt_f32_f16_sdwa v193, v156 dst_sel:DWORD dst_unused:UNUSED_PAD src0_sel:WORD_1
	v_cvt_f32_f16_sdwa v189, v158 dst_sel:DWORD dst_unused:UNUSED_PAD src0_sel:WORD_1
	v_cvt_f32_f16_e32 v194, v157
	v_cvt_f32_f16_e32 v190, v159
	v_cvt_f32_f16_sdwa v195, v157 dst_sel:DWORD dst_unused:UNUSED_PAD src0_sel:WORD_1
	v_cvt_f32_f16_sdwa v191, v159 dst_sel:DWORD dst_unused:UNUSED_PAD src0_sel:WORD_1
	v_cvt_f32_f16_e32 v184, v160
	v_cvt_f32_f16_e32 v180, v162
	v_cvt_f32_f16_sdwa v185, v160 dst_sel:DWORD dst_unused:UNUSED_PAD src0_sel:WORD_1
	v_cvt_f32_f16_sdwa v181, v162 dst_sel:DWORD dst_unused:UNUSED_PAD src0_sel:WORD_1
	v_cvt_f32_f16_e32 v186, v161
	v_cvt_f32_f16_e32 v182, v163
	v_cvt_f32_f16_sdwa v187, v161 dst_sel:DWORD dst_unused:UNUSED_PAD src0_sel:WORD_1
	v_cvt_f32_f16_sdwa v183, v163 dst_sel:DWORD dst_unused:UNUSED_PAD src0_sel:WORD_1
	v_lshl_or_b32 v142, s45, 8, v215
	s_mov_b64 s[44:45], -1
	v_ashrrev_i32_e32 v143, 31, v142
	s_mov_b64 vcc, s[4:5]
	s_waitcnt vmcnt(3)
	v_cvt_f32_f16_e32 v176, v164
	v_cvt_f32_f16_e32 v172, v166
	v_cvt_f32_f16_sdwa v177, v164 dst_sel:DWORD dst_unused:UNUSED_PAD src0_sel:WORD_1
	v_cvt_f32_f16_sdwa v173, v166 dst_sel:DWORD dst_unused:UNUSED_PAD src0_sel:WORD_1
	v_cvt_f32_f16_e32 v178, v165
	v_cvt_f32_f16_e32 v174, v167
	v_cvt_f32_f16_sdwa v179, v165 dst_sel:DWORD dst_unused:UNUSED_PAD src0_sel:WORD_1
	v_cvt_f32_f16_sdwa v175, v167 dst_sel:DWORD dst_unused:UNUSED_PAD src0_sel:WORD_1
	s_waitcnt vmcnt(2)
	v_cvt_f32_f16_e32 v168, v218
	v_cvt_f32_f16_e32 v164, v220
	v_cvt_f32_f16_sdwa v169, v218 dst_sel:DWORD dst_unused:UNUSED_PAD src0_sel:WORD_1
	v_cvt_f32_f16_sdwa v165, v220 dst_sel:DWORD dst_unused:UNUSED_PAD src0_sel:WORD_1
	v_cvt_f32_f16_e32 v170, v219
	v_cvt_f32_f16_e32 v166, v221
	v_cvt_f32_f16_sdwa v171, v219 dst_sel:DWORD dst_unused:UNUSED_PAD src0_sel:WORD_1
	v_cvt_f32_f16_sdwa v167, v221 dst_sel:DWORD dst_unused:UNUSED_PAD src0_sel:WORD_1
	s_waitcnt vmcnt(1)
	v_cvt_f32_f16_e32 v160, v222
	v_cvt_f32_f16_e32 v156, v224
	v_cvt_f32_f16_sdwa v161, v222 dst_sel:DWORD dst_unused:UNUSED_PAD src0_sel:WORD_1
	v_cvt_f32_f16_sdwa v157, v224 dst_sel:DWORD dst_unused:UNUSED_PAD src0_sel:WORD_1
	v_cvt_f32_f16_e32 v162, v223
	v_cvt_f32_f16_e32 v158, v225
	v_cvt_f32_f16_sdwa v163, v223 dst_sel:DWORD dst_unused:UNUSED_PAD src0_sel:WORD_1
	v_cvt_f32_f16_sdwa v159, v225 dst_sel:DWORD dst_unused:UNUSED_PAD src0_sel:WORD_1
	s_waitcnt vmcnt(0)
	v_cvt_f32_f16_e32 v152, v226
	v_cvt_f32_f16_e32 v148, v228
	v_cvt_f32_f16_sdwa v153, v226 dst_sel:DWORD dst_unused:UNUSED_PAD src0_sel:WORD_1
	v_cvt_f32_f16_sdwa v149, v228 dst_sel:DWORD dst_unused:UNUSED_PAD src0_sel:WORD_1
	v_cvt_f32_f16_e32 v154, v227
	v_cvt_f32_f16_e32 v150, v229
	v_cvt_f32_f16_sdwa v155, v227 dst_sel:DWORD dst_unused:UNUSED_PAD src0_sel:WORD_1
	v_cvt_f32_f16_sdwa v151, v229 dst_sel:DWORD dst_unused:UNUSED_PAD src0_sel:WORD_1
	s_cbranch_vccnz .LBB0_476
;     __device__ __forceinline__ void operator()(f32x4 (&acc)[2][2][4][2], const Unit& u, int wr, int wc, int fr, int fq) const {
;     ...
;                 for (int m = 0; m < 4; ++m) { const size_t row = (size_t)(row0 + ai * HALF + m * 16);
; #pragma unroll
;                     for (int bj = 0; bj < 2; ++bj) { const int col = col0 + bj * HALF;
;                         float o[8];
; #pragma unroll
;                         for (int j = 0; j < 4; ++j) { o[j] = acc[ai][bj][m][0][j] * (float)gt[m][bj][j]; o[4 + j] = acc[ai][bj][m][1][j] * (float)gt[m][bj][4 + j]; }
;                         u32x4 w; w.x = pkg(o[0], o[1]); w.y = pkg(o[2], o[3]); w.z = pkg(o[4], o[5]); w.w = pkg(o[6], o[7]);
;                         *(u32x4*)(MG + row * D + col) = w; } }
	v_lshlrev_b64 v[222:223], 13, v[144:145]
	v_mul_f32_e32 v220, v120, v204
	v_mul_f32_e32 v221, v121, v205
	v_mul_f32_e32 v219, v126, v210
	v_mul_f32_e32 v224, v122, v206
	v_mul_f32_e32 v225, v127, v211
	v_mul_f32_e32 v218, v125, v209
	v_mul_f32_e32 v226, v123, v207
	v_cvt_pk_bf16_f32 v219, v219, v225
	v_cvt_pk_bf16_f32 v220, v220, v221
	v_cvt_pk_bf16_f32 v221, v224, v226
	v_lshl_add_u64 v[222:223], s[12:13], 0, v[222:223]
	v_lshlrev_b64 v[224:225], 1, v[142:143]
	v_mul_f32_e32 v217, v124, v208
	v_cvt_pk_bf16_f32 v218, v217, v218
	v_lshl_add_u64 v[222:223], v[222:223], 0, v[224:225]
	global_store_dwordx4 v[222:223], v[218:221], off
	v_mul_f32_e32 v217, v92, v200
	v_mul_f32_e32 v226, v90, v198
	v_mul_f32_e32 v218, v93, v201
	v_mul_f32_e32 v220, v88, v196
	v_mul_f32_e32 v221, v89, v197
	v_mul_f32_e32 v219, v94, v202
	v_cvt_pk_bf16_f32 v218, v217, v218
	v_mul_f32_e32 v227, v95, v203
	v_mul_f32_e32 v228, v91, v199
	v_cvt_pk_bf16_f32 v219, v219, v227
	v_cvt_pk_bf16_f32 v220, v220, v221
	v_cvt_pk_bf16_f32 v221, v226, v228
	global_store_dwordx4 v[222:223], v[218:221], off offset:256
	v_mul_f32_e32 v217, v116, v192
	v_mul_f32_e32 v226, v114, v190
	v_or_b32_e32 v218, 16, v144
	v_ashrrev_i32_e32 v219, 31, v218
	v_lshlrev_b64 v[222:223], 13, v[218:219]
	v_mul_f32_e32 v218, v117, v193
	v_lshl_add_u64 v[222:223], s[12:13], 0, v[222:223]
	v_mul_f32_e32 v220, v112, v188
	v_mul_f32_e32 v221, v113, v189
	v_mul_f32_e32 v219, v118, v194
	v_cvt_pk_bf16_f32 v218, v217, v218
	v_lshl_add_u64 v[222:223], v[222:223], 0, v[224:225]
	v_mul_f32_e32 v227, v119, v195
	v_mul_f32_e32 v228, v115, v191
	v_cvt_pk_bf16_f32 v219, v219, v227
	v_cvt_pk_bf16_f32 v220, v220, v221
	v_cvt_pk_bf16_f32 v221, v226, v228
	global_store_dwordx4 v[222:223], v[218:221], off
	v_mul_f32_e32 v217, v84, v184
	v_mul_f32_e32 v226, v82, v182
	v_mul_f32_e32 v218, v85, v185
	v_mul_f32_e32 v220, v80, v180
	v_mul_f32_e32 v221, v81, v181
	v_mul_f32_e32 v219, v86, v186
	v_cvt_pk_bf16_f32 v218, v217, v218
	v_mul_f32_e32 v227, v87, v187
	v_mul_f32_e32 v228, v83, v183
	v_cvt_pk_bf16_f32 v219, v219, v227
	v_cvt_pk_bf16_f32 v220, v220, v221
	v_cvt_pk_bf16_f32 v221, v226, v228
	global_store_dwordx4 v[222:223], v[218:221], off offset:256
	v_mul_f32_e32 v217, v108, v176
	v_mul_f32_e32 v226, v106, v174
	v_or_b32_e32 v218, 32, v144
	v_ashrrev_i32_e32 v219, 31, v218
	v_lshlrev_b64 v[222:223], 13, v[218:219]
	v_mul_f32_e32 v218, v109, v177
	v_lshl_add_u64 v[222:223], s[12:13], 0, v[222:223]
	v_mul_f32_e32 v220, v104, v172
	v_mul_f32_e32 v221, v105, v173
	v_mul_f32_e32 v219, v110, v178
	v_cvt_pk_bf16_f32 v218, v217, v218
	v_lshl_add_u64 v[222:223], v[222:223], 0, v[224:225]
	v_mul_f32_e32 v227, v111, v179
	v_mul_f32_e32 v228, v107, v175
	v_cvt_pk_bf16_f32 v219, v219, v227
	v_cvt_pk_bf16_f32 v220, v220, v221
	v_cvt_pk_bf16_f32 v221, v226, v228
	global_store_dwordx4 v[222:223], v[218:221], off
	v_mul_f32_e32 v217, v76, v168
	v_mul_f32_e32 v226, v74, v166
	v_mul_f32_e32 v218, v77, v169
	v_mul_f32_e32 v220, v72, v164
	v_mul_f32_e32 v221, v73, v165
	v_mul_f32_e32 v219, v78, v170
	v_cvt_pk_bf16_f32 v218, v217, v218
	v_mul_f32_e32 v227, v79, v171
	v_mul_f32_e32 v228, v75, v167
	v_cvt_pk_bf16_f32 v219, v219, v227
	v_cvt_pk_bf16_f32 v220, v220, v221
	v_cvt_pk_bf16_f32 v221, v226, v228
	global_store_dwordx4 v[222:223], v[218:221], off offset:256
	v_mul_f32_e32 v217, v100, v160
	v_mul_f32_e32 v226, v98, v158
	v_or_b32_e32 v218, 48, v144
	v_ashrrev_i32_e32 v219, 31, v218
	v_lshlrev_b64 v[222:223], 13, v[218:219]
	v_mul_f32_e32 v220, v96, v156
	v_mul_f32_e32 v218, v101, v161
	v_mul_f32_e32 v221, v97, v157
	v_mul_f32_e32 v219, v102, v162
	v_lshl_add_u64 v[222:223], s[12:13], 0, v[222:223]
	v_mul_f32_e32 v227, v103, v163
	v_mul_f32_e32 v228, v99, v159
	v_cvt_pk_bf16_f32 v218, v217, v218
	v_cvt_pk_bf16_f32 v219, v219, v227
	v_cvt_pk_bf16_f32 v220, v220, v221
	v_cvt_pk_bf16_f32 v221, v226, v228
	v_lshl_add_u64 v[222:223], v[222:223], 0, v[224:225]
	global_store_dwordx4 v[222:223], v[218:221], off
	s_mov_b64 s[44:45], 0
	v_mul_f32_e32 v217, v68, v152
	v_mul_f32_e32 v220, v64, v148
	v_mul_f32_e32 v218, v69, v153
	v_mul_f32_e32 v221, v65, v149
	v_mul_f32_e32 v219, v70, v154
	v_mul_f32_e32 v224, v66, v150
	v_mul_f32_e32 v225, v71, v155
	v_mul_f32_e32 v226, v67, v151
	v_cvt_pk_bf16_f32 v218, v217, v218
	v_cvt_pk_bf16_f32 v219, v219, v225
	v_cvt_pk_bf16_f32 v220, v220, v221
	v_cvt_pk_bf16_f32 v221, v224, v226
	global_store_dwordx4 v[222:223], v[218:221], off offset:256
